# FFN-down epilogue: each group's four 8-byte stores widened to two 16-byte stores with v_permlane16_swap (same bytes, same addresses)
# speedup vs baseline: 1.0092x; 1.0052x over previous
.LBB0_659:
	v_mbcnt_lo_u32_b32 v250, -1, 0
	v_mbcnt_hi_u32_b32 v250, -1, v250
	v_and_b32_e32 v250, 16, v250
	v_mul_u32_u24_e32 v250, 3, v250
	v_lshrrev_b32_e32 v250, 1, v250
	v_mov_b32_e32 v251, 0
	v_lshl_add_u32 v144, s45, 8, v146
	v_lshl_or_b32 v142, s46, 8, v148
	v_ashrrev_i32_e32 v145, 31, v144
	v_ashrrev_i32_e32 v143, 31, v142
	v_lshlrev_b64 v[140:141], 10, v[144:145]
	v_lshl_add_u64 v[140:141], v[140:141], 0, v[142:143]
	v_lshlrev_b64 v[140:141], 1, v[140:141]
	v_lshl_add_u64 v[152:153], s[64:65], 0, v[140:141]
	global_load_dwordx2 v[154:155], v[152:153], off
	global_load_dwordx2 v[156:157], v[152:153], off offset:32
	global_load_dwordx2 v[158:159], v[152:153], off offset:256
	s_nop 0
	global_load_dwordx2 v[152:153], v[152:153], off offset:288
	v_or_b32_e32 v160, 16, v144
	v_ashrrev_i32_e32 v161, 31, v160
	v_lshlrev_b64 v[160:161], 10, v[160:161]
	v_lshl_add_u64 v[160:161], v[160:161], 0, v[142:143]
	v_lshl_add_u64 v[162:163], s[62:63], 0, v[140:141]
	v_lshlrev_b64 v[160:161], 1, v[160:161]
	v_lshl_add_u64 v[164:165], s[64:65], 0, v[160:161]
	s_and_b64 vcc, exec, s[2:3]
	s_mov_b64 s[2:3], -1
	s_waitcnt vmcnt(0)
	v_lshlrev_b32_e32 v166, 16, v154
	v_and_b32_e32 v167, 0xffff0000, v154
	v_lshlrev_b32_e32 v154, 16, v155
	v_and_b32_e32 v155, 0xffff0000, v155
	v_lshlrev_b32_e32 v168, 16, v156
	v_and_b32_e32 v169, 0xffff0000, v156
	v_lshlrev_b32_e32 v156, 16, v157
	v_and_b32_e32 v157, 0xffff0000, v157
	v_lshlrev_b32_e32 v170, 16, v158
	v_and_b32_e32 v171, 0xffff0000, v158
	v_lshlrev_b32_e32 v158, 16, v159
	v_and_b32_e32 v159, 0xffff0000, v159
	v_lshlrev_b32_e32 v172, 16, v152
	v_and_b32_e32 v173, 0xffff0000, v152
	v_lshlrev_b32_e32 v152, 16, v153
	v_and_b32_e32 v153, 0xffff0000, v153
	v_pk_fma_f32 v[126:127], v[154:155], s[10:11], v[126:127] op_sel_hi:[1,0,1]
	v_pk_fma_f32 v[124:125], v[166:167], s[10:11], v[124:125] op_sel_hi:[1,0,1]
	v_pk_fma_f32 v[122:123], v[156:157], s[10:11], v[122:123] op_sel_hi:[1,0,1]
	v_pk_fma_f32 v[120:121], v[168:169], s[10:11], v[120:121] op_sel_hi:[1,0,1]
	v_pk_fma_f32 v[118:119], v[158:159], s[10:11], v[118:119] op_sel_hi:[1,0,1]
	v_pk_fma_f32 v[116:117], v[170:171], s[10:11], v[116:117] op_sel_hi:[1,0,1]
	v_pk_fma_f32 v[114:115], v[152:153], s[10:11], v[114:115] op_sel_hi:[1,0,1]
	v_pk_fma_f32 v[112:113], v[172:173], s[10:11], v[112:113] op_sel_hi:[1,0,1]
	v_cvt_pk_bf16_f32 v124, v124, v125
	v_cvt_pk_bf16_f32 v125, v126, v127
	v_cvt_pk_bf16_f32 v126, v120, v121
	v_cvt_pk_bf16_f32 v127, v122, v123
	v_cvt_pk_bf16_f32 v116, v116, v117
	v_cvt_pk_bf16_f32 v117, v118, v119
	v_cvt_pk_bf16_f32 v118, v112, v113
	v_cvt_pk_bf16_f32 v119, v114, v115
	v_lshl_add_u64 v[162:163], v[162:163], 0, v[250:251]
	s_nop 0
	v_permlane16_swap_b32 v124, v126
	v_permlane16_swap_b32 v125, v127
	v_permlane16_swap_b32 v116, v118
	v_permlane16_swap_b32 v117, v119
	global_store_dwordx4 v[162:163], v[124:127], off
	global_store_dwordx4 v[162:163], v[116:119], off offset:256
	s_nop 0
	global_load_dwordx2 v[112:113], v[164:165], off
	s_nop 0
	global_load_dwordx2 v[114:115], v[164:165], off offset:32
	global_load_dwordx2 v[116:117], v[164:165], off offset:256
	global_load_dwordx2 v[118:119], v[164:165], off offset:288
	v_or_b32_e32 v120, 32, v144
	v_ashrrev_i32_e32 v121, 31, v120
	v_lshlrev_b64 v[120:121], 10, v[120:121]
	v_lshl_add_u64 v[120:121], v[120:121], 0, v[142:143]
	v_lshlrev_b64 v[120:121], 1, v[120:121]
	v_lshl_add_u64 v[122:123], s[62:63], 0, v[160:161]
	v_lshl_add_u64 v[124:125], s[64:65], 0, v[120:121]
	s_waitcnt vmcnt(3)
	v_lshlrev_b32_e32 v126, 16, v112
	v_and_b32_e32 v127, 0xffff0000, v112
	v_lshlrev_b32_e32 v112, 16, v113
	v_and_b32_e32 v113, 0xffff0000, v113
	s_waitcnt vmcnt(2)
	v_lshlrev_b32_e32 v152, 16, v114
	v_and_b32_e32 v153, 0xffff0000, v114
	v_lshlrev_b32_e32 v114, 16, v115
	v_and_b32_e32 v115, 0xffff0000, v115
	s_waitcnt vmcnt(1)
	v_lshlrev_b32_e32 v154, 16, v116
	v_and_b32_e32 v155, 0xffff0000, v116
	v_lshlrev_b32_e32 v116, 16, v117
	v_and_b32_e32 v117, 0xffff0000, v117
	s_waitcnt vmcnt(0)
	v_lshlrev_b32_e32 v156, 16, v118
	v_and_b32_e32 v157, 0xffff0000, v118
	v_lshlrev_b32_e32 v118, 16, v119
	v_and_b32_e32 v119, 0xffff0000, v119
	v_pk_fma_f32 v[110:111], v[112:113], s[10:11], v[110:111] op_sel_hi:[1,0,1]
	v_pk_fma_f32 v[108:109], v[126:127], s[10:11], v[108:109] op_sel_hi:[1,0,1]
	v_pk_fma_f32 v[106:107], v[114:115], s[10:11], v[106:107] op_sel_hi:[1,0,1]
	v_pk_fma_f32 v[104:105], v[152:153], s[10:11], v[104:105] op_sel_hi:[1,0,1]
	v_pk_fma_f32 v[102:103], v[116:117], s[10:11], v[102:103] op_sel_hi:[1,0,1]
	v_pk_fma_f32 v[100:101], v[154:155], s[10:11], v[100:101] op_sel_hi:[1,0,1]
	v_pk_fma_f32 v[98:99], v[118:119], s[10:11], v[98:99] op_sel_hi:[1,0,1]
	v_pk_fma_f32 v[96:97], v[156:157], s[10:11], v[96:97] op_sel_hi:[1,0,1]
	v_cvt_pk_bf16_f32 v108, v108, v109
	v_cvt_pk_bf16_f32 v109, v110, v111
	v_cvt_pk_bf16_f32 v110, v104, v105
	v_cvt_pk_bf16_f32 v111, v106, v107
	v_cvt_pk_bf16_f32 v100, v100, v101
	v_cvt_pk_bf16_f32 v101, v102, v103
	v_cvt_pk_bf16_f32 v102, v96, v97
	v_cvt_pk_bf16_f32 v103, v98, v99
	v_lshl_add_u64 v[122:123], v[122:123], 0, v[250:251]
	s_nop 0
	v_permlane16_swap_b32 v108, v110
	v_permlane16_swap_b32 v109, v111
	v_permlane16_swap_b32 v100, v102
	v_permlane16_swap_b32 v101, v103
	global_store_dwordx4 v[122:123], v[108:111], off
	global_store_dwordx4 v[122:123], v[100:103], off offset:256
	s_nop 0
	global_load_dwordx2 v[96:97], v[124:125], off
	s_nop 0
	global_load_dwordx2 v[98:99], v[124:125], off offset:32
	global_load_dwordx2 v[100:101], v[124:125], off offset:256
	global_load_dwordx2 v[102:103], v[124:125], off offset:288
	v_or_b32_e32 v104, 48, v144
	v_ashrrev_i32_e32 v105, 31, v104
	v_lshlrev_b64 v[104:105], 10, v[104:105]
	v_lshl_add_u64 v[104:105], v[104:105], 0, v[142:143]
	v_lshlrev_b64 v[104:105], 1, v[104:105]
	v_lshl_add_u64 v[106:107], s[62:63], 0, v[120:121]
	v_lshl_add_u64 v[108:109], s[64:65], 0, v[104:105]
	s_waitcnt vmcnt(3)
	v_lshlrev_b32_e32 v110, 16, v96
	v_and_b32_e32 v111, 0xffff0000, v96
	v_lshlrev_b32_e32 v96, 16, v97
	v_and_b32_e32 v97, 0xffff0000, v97
	s_waitcnt vmcnt(2)
	v_lshlrev_b32_e32 v112, 16, v98
	v_and_b32_e32 v113, 0xffff0000, v98
	v_lshlrev_b32_e32 v98, 16, v99
	v_and_b32_e32 v99, 0xffff0000, v99
	s_waitcnt vmcnt(1)
	v_lshlrev_b32_e32 v114, 16, v100
	v_and_b32_e32 v115, 0xffff0000, v100
	v_lshlrev_b32_e32 v100, 16, v101
	v_and_b32_e32 v101, 0xffff0000, v101
	s_waitcnt vmcnt(0)
	v_lshlrev_b32_e32 v116, 16, v102
	v_and_b32_e32 v117, 0xffff0000, v102
	v_lshlrev_b32_e32 v102, 16, v103
	v_and_b32_e32 v103, 0xffff0000, v103
	v_pk_fma_f32 v[94:95], v[96:97], s[10:11], v[94:95] op_sel_hi:[1,0,1]
	v_pk_fma_f32 v[92:93], v[110:111], s[10:11], v[92:93] op_sel_hi:[1,0,1]
	v_pk_fma_f32 v[90:91], v[98:99], s[10:11], v[90:91] op_sel_hi:[1,0,1]
	v_pk_fma_f32 v[88:89], v[112:113], s[10:11], v[88:89] op_sel_hi:[1,0,1]
	v_pk_fma_f32 v[86:87], v[100:101], s[10:11], v[86:87] op_sel_hi:[1,0,1]
	v_pk_fma_f32 v[84:85], v[114:115], s[10:11], v[84:85] op_sel_hi:[1,0,1]
	v_pk_fma_f32 v[82:83], v[102:103], s[10:11], v[82:83] op_sel_hi:[1,0,1]
	v_pk_fma_f32 v[80:81], v[116:117], s[10:11], v[80:81] op_sel_hi:[1,0,1]
	v_cvt_pk_bf16_f32 v92, v92, v93
	v_cvt_pk_bf16_f32 v93, v94, v95
	v_cvt_pk_bf16_f32 v94, v88, v89
	v_cvt_pk_bf16_f32 v95, v90, v91
	v_cvt_pk_bf16_f32 v84, v84, v85
	v_cvt_pk_bf16_f32 v85, v86, v87
	v_cvt_pk_bf16_f32 v86, v80, v81
	v_cvt_pk_bf16_f32 v87, v82, v83
	v_lshl_add_u64 v[106:107], v[106:107], 0, v[250:251]
	s_nop 0
	v_permlane16_swap_b32 v92, v94
	v_permlane16_swap_b32 v93, v95
	v_permlane16_swap_b32 v84, v86
	v_permlane16_swap_b32 v85, v87
	global_store_dwordx4 v[106:107], v[92:95], off
	global_store_dwordx4 v[106:107], v[84:87], off offset:256
	s_nop 0
	global_load_dwordx2 v[80:81], v[108:109], off
	s_nop 0
	global_load_dwordx2 v[82:83], v[108:109], off offset:32
	global_load_dwordx2 v[84:85], v[108:109], off offset:256
	global_load_dwordx2 v[86:87], v[108:109], off offset:288
	v_lshl_add_u64 v[88:89], v[140:141], 0, s[12:13]
	v_lshl_add_u64 v[90:91], s[62:63], 0, v[104:105]
	v_lshl_add_u64 v[92:93], s[64:65], 0, v[88:89]
	s_waitcnt vmcnt(3)
	v_lshlrev_b32_e32 v94, 16, v80
	v_and_b32_e32 v95, 0xffff0000, v80
	v_lshlrev_b32_e32 v80, 16, v81
	v_and_b32_e32 v81, 0xffff0000, v81
	s_waitcnt vmcnt(2)
	v_lshlrev_b32_e32 v96, 16, v82
	v_and_b32_e32 v97, 0xffff0000, v82
	v_lshlrev_b32_e32 v82, 16, v83
	v_and_b32_e32 v83, 0xffff0000, v83
	s_waitcnt vmcnt(1)
	v_lshlrev_b32_e32 v98, 16, v84
	v_and_b32_e32 v99, 0xffff0000, v84
	v_lshlrev_b32_e32 v84, 16, v85
	v_and_b32_e32 v85, 0xffff0000, v85
	s_waitcnt vmcnt(0)
	v_lshlrev_b32_e32 v100, 16, v86
	v_and_b32_e32 v101, 0xffff0000, v86
	v_lshlrev_b32_e32 v86, 16, v87
	v_and_b32_e32 v87, 0xffff0000, v87
	v_pk_fma_f32 v[78:79], v[80:81], s[10:11], v[78:79] op_sel_hi:[1,0,1]
	v_pk_fma_f32 v[76:77], v[94:95], s[10:11], v[76:77] op_sel_hi:[1,0,1]
	v_pk_fma_f32 v[74:75], v[82:83], s[10:11], v[74:75] op_sel_hi:[1,0,1]
	v_pk_fma_f32 v[72:73], v[96:97], s[10:11], v[72:73] op_sel_hi:[1,0,1]
	v_pk_fma_f32 v[70:71], v[84:85], s[10:11], v[70:71] op_sel_hi:[1,0,1]
	v_pk_fma_f32 v[68:69], v[98:99], s[10:11], v[68:69] op_sel_hi:[1,0,1]
	v_pk_fma_f32 v[66:67], v[86:87], s[10:11], v[66:67] op_sel_hi:[1,0,1]
	v_pk_fma_f32 v[64:65], v[100:101], s[10:11], v[64:65] op_sel_hi:[1,0,1]
	v_cvt_pk_bf16_f32 v76, v76, v77
	v_cvt_pk_bf16_f32 v77, v78, v79
	v_cvt_pk_bf16_f32 v78, v72, v73
	v_cvt_pk_bf16_f32 v79, v74, v75
	v_cvt_pk_bf16_f32 v68, v68, v69
	v_cvt_pk_bf16_f32 v69, v70, v71
	v_cvt_pk_bf16_f32 v70, v64, v65
	v_cvt_pk_bf16_f32 v71, v66, v67
	v_lshl_add_u64 v[90:91], v[90:91], 0, v[250:251]
	s_nop 0
	v_permlane16_swap_b32 v76, v78
	v_permlane16_swap_b32 v77, v79
	v_permlane16_swap_b32 v68, v70
	v_permlane16_swap_b32 v69, v71
	global_store_dwordx4 v[90:91], v[76:79], off
	global_store_dwordx4 v[90:91], v[68:71], off offset:256
	s_nop 0
	global_load_dwordx2 v[64:65], v[92:93], off
	s_nop 0
	global_load_dwordx2 v[66:67], v[92:93], off offset:32
	global_load_dwordx2 v[68:69], v[92:93], off offset:256
	global_load_dwordx2 v[70:71], v[92:93], off offset:288
	v_lshl_add_u64 v[72:73], v[140:141], 0, s[14:15]
	v_lshl_add_u64 v[74:75], s[62:63], 0, v[88:89]
	v_lshl_add_u64 v[76:77], s[64:65], 0, v[72:73]
	s_waitcnt vmcnt(3)
	v_lshlrev_b32_e32 v78, 16, v64
	v_and_b32_e32 v79, 0xffff0000, v64
	v_lshlrev_b32_e32 v64, 16, v65
	v_and_b32_e32 v65, 0xffff0000, v65
	s_waitcnt vmcnt(2)
	v_lshlrev_b32_e32 v80, 16, v66
	v_and_b32_e32 v81, 0xffff0000, v66
	v_lshlrev_b32_e32 v66, 16, v67
	v_and_b32_e32 v67, 0xffff0000, v67
	s_waitcnt vmcnt(1)
	v_lshlrev_b32_e32 v82, 16, v68
	v_and_b32_e32 v83, 0xffff0000, v68
	v_lshlrev_b32_e32 v68, 16, v69
	v_and_b32_e32 v69, 0xffff0000, v69
	s_waitcnt vmcnt(0)
	v_lshlrev_b32_e32 v84, 16, v70
	v_and_b32_e32 v85, 0xffff0000, v70
	v_lshlrev_b32_e32 v70, 16, v71
	v_and_b32_e32 v71, 0xffff0000, v71
	v_pk_fma_f32 v[62:63], v[64:65], s[10:11], v[62:63] op_sel_hi:[1,0,1]
	v_pk_fma_f32 v[60:61], v[78:79], s[10:11], v[60:61] op_sel_hi:[1,0,1]
	v_pk_fma_f32 v[58:59], v[66:67], s[10:11], v[58:59] op_sel_hi:[1,0,1]
	v_pk_fma_f32 v[56:57], v[80:81], s[10:11], v[56:57] op_sel_hi:[1,0,1]
	v_pk_fma_f32 v[54:55], v[68:69], s[10:11], v[54:55] op_sel_hi:[1,0,1]
	v_pk_fma_f32 v[52:53], v[82:83], s[10:11], v[52:53] op_sel_hi:[1,0,1]
	v_pk_fma_f32 v[50:51], v[70:71], s[10:11], v[50:51] op_sel_hi:[1,0,1]
	v_pk_fma_f32 v[48:49], v[84:85], s[10:11], v[48:49] op_sel_hi:[1,0,1]
	v_cvt_pk_bf16_f32 v60, v60, v61
	v_cvt_pk_bf16_f32 v61, v62, v63
	v_cvt_pk_bf16_f32 v62, v56, v57
	v_cvt_pk_bf16_f32 v63, v58, v59
	v_cvt_pk_bf16_f32 v52, v52, v53
	v_cvt_pk_bf16_f32 v53, v54, v55
	v_cvt_pk_bf16_f32 v54, v48, v49
	v_cvt_pk_bf16_f32 v55, v50, v51
	v_lshl_add_u64 v[74:75], v[74:75], 0, v[250:251]
	s_nop 0
	v_permlane16_swap_b32 v60, v62
	v_permlane16_swap_b32 v61, v63
	v_permlane16_swap_b32 v52, v54
	v_permlane16_swap_b32 v53, v55
	global_store_dwordx4 v[74:75], v[60:63], off
	global_store_dwordx4 v[74:75], v[52:55], off offset:256
	s_nop 0
	global_load_dwordx2 v[48:49], v[76:77], off
	s_nop 0
	global_load_dwordx2 v[50:51], v[76:77], off offset:32
	global_load_dwordx2 v[52:53], v[76:77], off offset:256
	global_load_dwordx2 v[54:55], v[76:77], off offset:288
	v_lshl_add_u64 v[56:57], v[140:141], 0, s[16:17]
	v_lshl_add_u64 v[58:59], s[62:63], 0, v[72:73]
	v_lshl_add_u64 v[60:61], s[64:65], 0, v[56:57]
	s_waitcnt vmcnt(3)
	v_lshlrev_b32_e32 v62, 16, v48
	v_and_b32_e32 v63, 0xffff0000, v48
	v_lshlrev_b32_e32 v48, 16, v49
	v_and_b32_e32 v49, 0xffff0000, v49
	s_waitcnt vmcnt(2)
	v_lshlrev_b32_e32 v64, 16, v50
	v_and_b32_e32 v65, 0xffff0000, v50
	v_lshlrev_b32_e32 v50, 16, v51
	v_and_b32_e32 v51, 0xffff0000, v51
	s_waitcnt vmcnt(1)
	v_lshlrev_b32_e32 v66, 16, v52
	v_and_b32_e32 v67, 0xffff0000, v52
	v_lshlrev_b32_e32 v52, 16, v53
	v_and_b32_e32 v53, 0xffff0000, v53
	s_waitcnt vmcnt(0)
	v_lshlrev_b32_e32 v68, 16, v54
	v_and_b32_e32 v69, 0xffff0000, v54
	v_lshlrev_b32_e32 v54, 16, v55
	v_and_b32_e32 v55, 0xffff0000, v55
	v_pk_fma_f32 v[46:47], v[48:49], s[10:11], v[46:47] op_sel_hi:[1,0,1]
	v_pk_fma_f32 v[44:45], v[62:63], s[10:11], v[44:45] op_sel_hi:[1,0,1]
	v_pk_fma_f32 v[42:43], v[50:51], s[10:11], v[42:43] op_sel_hi:[1,0,1]
	v_pk_fma_f32 v[40:41], v[64:65], s[10:11], v[40:41] op_sel_hi:[1,0,1]
	v_pk_fma_f32 v[38:39], v[52:53], s[10:11], v[38:39] op_sel_hi:[1,0,1]
	v_pk_fma_f32 v[36:37], v[66:67], s[10:11], v[36:37] op_sel_hi:[1,0,1]
	v_pk_fma_f32 v[34:35], v[54:55], s[10:11], v[34:35] op_sel_hi:[1,0,1]
	v_pk_fma_f32 v[32:33], v[68:69], s[10:11], v[32:33] op_sel_hi:[1,0,1]
	v_cvt_pk_bf16_f32 v44, v44, v45
	v_cvt_pk_bf16_f32 v45, v46, v47
	v_cvt_pk_bf16_f32 v46, v40, v41
	v_cvt_pk_bf16_f32 v47, v42, v43
	v_cvt_pk_bf16_f32 v36, v36, v37
	v_cvt_pk_bf16_f32 v37, v38, v39
	v_cvt_pk_bf16_f32 v38, v32, v33
	v_cvt_pk_bf16_f32 v39, v34, v35
	v_lshl_add_u64 v[58:59], v[58:59], 0, v[250:251]
	s_nop 0
	v_permlane16_swap_b32 v44, v46
	v_permlane16_swap_b32 v45, v47
	v_permlane16_swap_b32 v36, v38
	v_permlane16_swap_b32 v37, v39
	global_store_dwordx4 v[58:59], v[44:47], off
	global_store_dwordx4 v[58:59], v[36:39], off offset:256
	s_nop 0
	global_load_dwordx2 v[32:33], v[60:61], off
	s_nop 0
	global_load_dwordx2 v[34:35], v[60:61], off offset:32
	global_load_dwordx2 v[36:37], v[60:61], off offset:256
	global_load_dwordx2 v[38:39], v[60:61], off offset:288
	v_lshl_add_u64 v[40:41], v[140:141], 0, s[18:19]
	v_lshl_add_u64 v[42:43], s[62:63], 0, v[56:57]
	v_lshl_add_u64 v[44:45], s[64:65], 0, v[40:41]
	s_waitcnt vmcnt(3)
	v_lshlrev_b32_e32 v46, 16, v32
	v_and_b32_e32 v47, 0xffff0000, v32
	v_lshlrev_b32_e32 v32, 16, v33
	v_and_b32_e32 v33, 0xffff0000, v33
	s_waitcnt vmcnt(2)
	v_lshlrev_b32_e32 v48, 16, v34
	v_and_b32_e32 v49, 0xffff0000, v34
	v_lshlrev_b32_e32 v34, 16, v35
	v_and_b32_e32 v35, 0xffff0000, v35
	s_waitcnt vmcnt(1)
	v_lshlrev_b32_e32 v50, 16, v36
	v_and_b32_e32 v51, 0xffff0000, v36
	v_lshlrev_b32_e32 v36, 16, v37
	v_and_b32_e32 v37, 0xffff0000, v37
	s_waitcnt vmcnt(0)
	v_lshlrev_b32_e32 v52, 16, v38
	v_and_b32_e32 v53, 0xffff0000, v38
	v_lshlrev_b32_e32 v38, 16, v39
	v_and_b32_e32 v39, 0xffff0000, v39
	v_pk_fma_f32 v[30:31], v[32:33], s[10:11], v[30:31] op_sel_hi:[1,0,1]
	v_pk_fma_f32 v[28:29], v[46:47], s[10:11], v[28:29] op_sel_hi:[1,0,1]
	v_pk_fma_f32 v[26:27], v[34:35], s[10:11], v[26:27] op_sel_hi:[1,0,1]
	v_pk_fma_f32 v[24:25], v[48:49], s[10:11], v[24:25] op_sel_hi:[1,0,1]
	v_pk_fma_f32 v[22:23], v[36:37], s[10:11], v[22:23] op_sel_hi:[1,0,1]
	v_pk_fma_f32 v[20:21], v[50:51], s[10:11], v[20:21] op_sel_hi:[1,0,1]
	v_pk_fma_f32 v[18:19], v[38:39], s[10:11], v[18:19] op_sel_hi:[1,0,1]
	v_pk_fma_f32 v[16:17], v[52:53], s[10:11], v[16:17] op_sel_hi:[1,0,1]
	v_cvt_pk_bf16_f32 v28, v28, v29
	v_cvt_pk_bf16_f32 v29, v30, v31
	v_cvt_pk_bf16_f32 v30, v24, v25
	v_cvt_pk_bf16_f32 v31, v26, v27
	v_cvt_pk_bf16_f32 v20, v20, v21
	v_cvt_pk_bf16_f32 v21, v22, v23
	v_cvt_pk_bf16_f32 v22, v16, v17
	v_cvt_pk_bf16_f32 v23, v18, v19
	v_lshl_add_u64 v[42:43], v[42:43], 0, v[250:251]
	s_nop 0
	v_permlane16_swap_b32 v28, v30
	v_permlane16_swap_b32 v29, v31
	v_permlane16_swap_b32 v20, v22
	v_permlane16_swap_b32 v21, v23
	global_store_dwordx4 v[42:43], v[28:31], off
	global_store_dwordx4 v[42:43], v[20:23], off offset:256
	s_nop 0
	global_load_dwordx2 v[16:17], v[44:45], off
	s_nop 0
	global_load_dwordx2 v[18:19], v[44:45], off offset:32
	global_load_dwordx2 v[20:21], v[44:45], off offset:256
	global_load_dwordx2 v[22:23], v[44:45], off offset:288
	v_lshl_add_u64 v[24:25], s[62:63], 0, v[40:41]
	s_waitcnt vmcnt(3)
	v_lshlrev_b32_e32 v26, 16, v16
	v_and_b32_e32 v27, 0xffff0000, v16
	v_lshlrev_b32_e32 v16, 16, v17
	v_and_b32_e32 v17, 0xffff0000, v17
	s_waitcnt vmcnt(2)
	v_lshlrev_b32_e32 v28, 16, v18
	v_and_b32_e32 v29, 0xffff0000, v18
	v_lshlrev_b32_e32 v18, 16, v19
	v_and_b32_e32 v19, 0xffff0000, v19
	s_waitcnt vmcnt(1)
	v_lshlrev_b32_e32 v30, 16, v20
	v_and_b32_e32 v31, 0xffff0000, v20
	v_lshlrev_b32_e32 v20, 16, v21
	v_and_b32_e32 v21, 0xffff0000, v21
	s_waitcnt vmcnt(0)
	v_lshlrev_b32_e32 v32, 16, v22
	v_and_b32_e32 v33, 0xffff0000, v22
	v_lshlrev_b32_e32 v22, 16, v23
	v_and_b32_e32 v23, 0xffff0000, v23
	v_pk_fma_f32 v[14:15], v[16:17], s[10:11], v[14:15] op_sel_hi:[1,0,1]
	v_pk_fma_f32 v[12:13], v[26:27], s[10:11], v[12:13] op_sel_hi:[1,0,1]
	v_pk_fma_f32 v[10:11], v[18:19], s[10:11], v[10:11] op_sel_hi:[1,0,1]
	v_pk_fma_f32 v[8:9], v[28:29], s[10:11], v[8:9] op_sel_hi:[1,0,1]
	v_pk_fma_f32 v[6:7], v[20:21], s[10:11], v[6:7] op_sel_hi:[1,0,1]
	v_pk_fma_f32 v[4:5], v[30:31], s[10:11], v[4:5] op_sel_hi:[1,0,1]
	v_pk_fma_f32 v[2:3], v[22:23], s[10:11], v[2:3] op_sel_hi:[1,0,1]
	v_pk_fma_f32 v[0:1], v[32:33], s[10:11], v[0:1] op_sel_hi:[1,0,1]
	v_cvt_pk_bf16_f32 v12, v12, v13
	v_cvt_pk_bf16_f32 v13, v14, v15
	v_cvt_pk_bf16_f32 v14, v8, v9
	v_cvt_pk_bf16_f32 v15, v10, v11
	v_cvt_pk_bf16_f32 v4, v4, v5
	v_cvt_pk_bf16_f32 v5, v6, v7
	v_cvt_pk_bf16_f32 v6, v0, v1
	v_cvt_pk_bf16_f32 v7, v2, v3
	v_lshl_add_u64 v[24:25], v[24:25], 0, v[250:251]
	s_nop 0
	v_permlane16_swap_b32 v12, v14
	v_permlane16_swap_b32 v13, v15
	v_permlane16_swap_b32 v4, v6
	v_permlane16_swap_b32 v5, v7
	global_store_dwordx4 v[24:25], v[12:15], off
	global_store_dwordx4 v[24:25], v[4:7], off offset:256
	s_nop 0
	s_cbranch_vccnz .LBB0_644
	s_andn2_b64 vcc, exec, s[0:1]
	s_cbranch_vccnz .LBB0_643
	s_barrier
	s_branch .LBB0_643
